# GEMM2 epilogue: gate/x loads batched (8 rounds, double-buffered) instead of a 32-step vmcnt(0) ladder
# speedup vs baseline: 1.1629x; 1.0160x over previous
.LBB0_163:
	v_add_u32_e32 v139, s37, v151
	v_or_b32_e32 v138, v139, v148
	v_ashrrev_i32_e32 v139, 13, v139
	v_mul_i32_i24_e32 v140, 0x3000, v139
	v_ashrrev_i32_e32 v141, 31, v140
	v_or_b32_e32 v174, s38, v152
	v_lshl_add_u64 v[140:141], v[140:141], 2, s[8:9]
	v_ashrrev_i32_e32 v139, 31, v138
	v_lshl_add_u64 v[176:177], v[140:141], 0, s[26:27]
	v_lshlrev_b64 v[140:141], 13, v[138:139]
	v_ashrrev_i32_e32 v175, 31, v174
	v_lshl_add_u64 v[140:141], s[6:7], 0, v[140:141]
	v_lshlrev_b64 v[142:143], 2, v[174:175]
	v_lshl_add_u64 v[180:181], v[140:141], 0, v[142:143]
	v_lshl_add_u64 v[140:141], v[176:177], 0, v[142:143]
	v_lshlrev_b64 v[182:183], 12, v[138:139]
	v_lshlrev_b64 v[144:145], 1, v[174:175]
	v_lshl_add_u64 v[182:183], s[10:11], 0, v[182:183]
	v_lshl_add_u64 v[182:183], v[182:183], 0, v[144:145]
	s_mov_b32 s48, 0x40000
	s_mov_b32 s49, 0
	s_mov_b32 s50, 0x20000
	s_mov_b32 s51, 0
	global_load_dwordx4 v[188:191], v[140:141], off offset:0
	global_load_dwordx4 v[192:195], v[140:141], off offset:32
	global_load_dwordx4 v[196:199], v[140:141], off offset:64
	global_load_dwordx4 v[200:203], v[140:141], off offset:96
	global_load_dwordx4 v[204:207], v[140:141], off offset:128
	global_load_dwordx4 v[208:211], v[140:141], off offset:160
	global_load_dwordx4 v[212:215], v[140:141], off offset:192
	global_load_dwordx4 v[216:219], v[140:141], off offset:224
	global_load_dwordx4 v[220:223], v[180:181], off offset:0
	global_load_dwordx4 v[224:227], v[180:181], off offset:32
	global_load_dwordx4 v[228:231], v[180:181], off offset:64
	global_load_dwordx4 v[232:235], v[180:181], off offset:96
	global_load_dwordx4 v[236:239], v[180:181], off offset:128
	global_load_dwordx4 v[244:247], v[180:181], off offset:160
	global_load_dwordx4 v[248:251], v[180:181], off offset:192
	global_load_dwordx4 v[252:255], v[180:181], off offset:224
	s_waitcnt vmcnt(4)
	v_pk_fma_f32 v[112:113], v[112:113], v[188:189], v[220:221]
	v_pk_fma_f32 v[114:115], v[114:115], v[190:191], v[222:223]
	v_pk_fma_f32 v[116:117], v[116:117], v[192:193], v[224:225]
	v_pk_fma_f32 v[118:119], v[118:119], v[194:195], v[226:227]
	v_pk_fma_f32 v[120:121], v[120:121], v[196:197], v[228:229]
	v_pk_fma_f32 v[122:123], v[122:123], v[198:199], v[230:231]
	v_pk_fma_f32 v[124:125], v[124:125], v[200:201], v[232:233]
	v_pk_fma_f32 v[126:127], v[126:127], v[202:203], v[234:235]
	v_cvt_pk_bf16_f32 v112, v112, v113
	v_cvt_pk_bf16_f32 v113, v114, v115
	v_cvt_pk_bf16_f32 v116, v116, v117
	v_cvt_pk_bf16_f32 v117, v118, v119
	v_cvt_pk_bf16_f32 v120, v120, v121
	v_cvt_pk_bf16_f32 v121, v122, v123
	v_cvt_pk_bf16_f32 v124, v124, v125
	v_cvt_pk_bf16_f32 v125, v126, v127
	global_store_dwordx2 v[182:183], v[112:113], off offset:0
	global_store_dwordx2 v[182:183], v[116:117], off offset:16
	global_store_dwordx2 v[182:183], v[120:121], off offset:32
	global_store_dwordx2 v[182:183], v[124:125], off offset:48
	v_lshl_add_u64 v[180:181], v[180:181], 0, s[48:49]
	global_load_dwordx4 v[220:223], v[180:181], off offset:0
	global_load_dwordx4 v[224:227], v[180:181], off offset:32
	global_load_dwordx4 v[228:231], v[180:181], off offset:64
	global_load_dwordx4 v[232:235], v[180:181], off offset:96
	s_waitcnt vmcnt(8)
	v_pk_fma_f32 v[96:97], v[96:97], v[204:205], v[236:237]
	v_pk_fma_f32 v[98:99], v[98:99], v[206:207], v[238:239]
	v_pk_fma_f32 v[100:101], v[100:101], v[208:209], v[244:245]
	v_pk_fma_f32 v[102:103], v[102:103], v[210:211], v[246:247]
	v_pk_fma_f32 v[104:105], v[104:105], v[212:213], v[248:249]
	v_pk_fma_f32 v[106:107], v[106:107], v[214:215], v[250:251]
	v_pk_fma_f32 v[108:109], v[108:109], v[216:217], v[252:253]
	v_pk_fma_f32 v[110:111], v[110:111], v[218:219], v[254:255]
	v_cvt_pk_bf16_f32 v96, v96, v97
	v_cvt_pk_bf16_f32 v97, v98, v99
	v_cvt_pk_bf16_f32 v100, v100, v101
	v_cvt_pk_bf16_f32 v101, v102, v103
	v_cvt_pk_bf16_f32 v104, v104, v105
	v_cvt_pk_bf16_f32 v105, v106, v107
	v_cvt_pk_bf16_f32 v108, v108, v109
	v_cvt_pk_bf16_f32 v109, v110, v111
	global_store_dwordx2 v[182:183], v[96:97], off offset:64
	global_store_dwordx2 v[182:183], v[100:101], off offset:80
	global_store_dwordx2 v[182:183], v[104:105], off offset:96
	global_store_dwordx2 v[182:183], v[108:109], off offset:112
	v_lshl_add_u64 v[182:183], v[182:183], 0, s[50:51]
	global_load_dwordx4 v[236:239], v[180:181], off offset:128
	global_load_dwordx4 v[244:247], v[180:181], off offset:160
	global_load_dwordx4 v[248:251], v[180:181], off offset:192
	global_load_dwordx4 v[252:255], v[180:181], off offset:224
	s_waitcnt vmcnt(8)
	v_pk_fma_f32 v[80:81], v[80:81], v[188:189], v[220:221]
	v_pk_fma_f32 v[82:83], v[82:83], v[190:191], v[222:223]
	v_pk_fma_f32 v[84:85], v[84:85], v[192:193], v[224:225]
	v_pk_fma_f32 v[86:87], v[86:87], v[194:195], v[226:227]
	v_pk_fma_f32 v[88:89], v[88:89], v[196:197], v[228:229]
	v_pk_fma_f32 v[90:91], v[90:91], v[198:199], v[230:231]
	v_pk_fma_f32 v[92:93], v[92:93], v[200:201], v[232:233]
	v_pk_fma_f32 v[94:95], v[94:95], v[202:203], v[234:235]
	v_cvt_pk_bf16_f32 v80, v80, v81
	v_cvt_pk_bf16_f32 v81, v82, v83
	v_cvt_pk_bf16_f32 v84, v84, v85
	v_cvt_pk_bf16_f32 v85, v86, v87
	v_cvt_pk_bf16_f32 v88, v88, v89
	v_cvt_pk_bf16_f32 v89, v90, v91
	v_cvt_pk_bf16_f32 v92, v92, v93
	v_cvt_pk_bf16_f32 v93, v94, v95
	global_store_dwordx2 v[182:183], v[80:81], off offset:0
	global_store_dwordx2 v[182:183], v[84:85], off offset:16
	global_store_dwordx2 v[182:183], v[88:89], off offset:32
	global_store_dwordx2 v[182:183], v[92:93], off offset:48
	v_lshl_add_u64 v[180:181], v[180:181], 0, s[48:49]
	global_load_dwordx4 v[220:223], v[180:181], off offset:0
	global_load_dwordx4 v[224:227], v[180:181], off offset:32
	global_load_dwordx4 v[228:231], v[180:181], off offset:64
	global_load_dwordx4 v[232:235], v[180:181], off offset:96
	s_waitcnt vmcnt(8)
	v_pk_fma_f32 v[64:65], v[64:65], v[204:205], v[236:237]
	v_pk_fma_f32 v[66:67], v[66:67], v[206:207], v[238:239]
	v_pk_fma_f32 v[68:69], v[68:69], v[208:209], v[244:245]
	v_pk_fma_f32 v[70:71], v[70:71], v[210:211], v[246:247]
	v_pk_fma_f32 v[72:73], v[72:73], v[212:213], v[248:249]
	v_pk_fma_f32 v[74:75], v[74:75], v[214:215], v[250:251]
	v_pk_fma_f32 v[76:77], v[76:77], v[216:217], v[252:253]
	v_pk_fma_f32 v[78:79], v[78:79], v[218:219], v[254:255]
	v_cvt_pk_bf16_f32 v64, v64, v65
	v_cvt_pk_bf16_f32 v65, v66, v67
	v_cvt_pk_bf16_f32 v68, v68, v69
	v_cvt_pk_bf16_f32 v69, v70, v71
	v_cvt_pk_bf16_f32 v72, v72, v73
	v_cvt_pk_bf16_f32 v73, v74, v75
	v_cvt_pk_bf16_f32 v76, v76, v77
	v_cvt_pk_bf16_f32 v77, v78, v79
	global_store_dwordx2 v[182:183], v[64:65], off offset:64
	global_store_dwordx2 v[182:183], v[68:69], off offset:80
	global_store_dwordx2 v[182:183], v[72:73], off offset:96
	global_store_dwordx2 v[182:183], v[76:77], off offset:112
	v_lshl_add_u64 v[182:183], v[182:183], 0, s[50:51]
	global_load_dwordx4 v[236:239], v[180:181], off offset:128
	global_load_dwordx4 v[244:247], v[180:181], off offset:160
	global_load_dwordx4 v[248:251], v[180:181], off offset:192
	global_load_dwordx4 v[252:255], v[180:181], off offset:224
	s_waitcnt vmcnt(8)
	v_pk_fma_f32 v[48:49], v[48:49], v[188:189], v[220:221]
	v_pk_fma_f32 v[50:51], v[50:51], v[190:191], v[222:223]
	v_pk_fma_f32 v[52:53], v[52:53], v[192:193], v[224:225]
	v_pk_fma_f32 v[54:55], v[54:55], v[194:195], v[226:227]
	v_pk_fma_f32 v[56:57], v[56:57], v[196:197], v[228:229]
	v_pk_fma_f32 v[58:59], v[58:59], v[198:199], v[230:231]
	v_pk_fma_f32 v[60:61], v[60:61], v[200:201], v[232:233]
	v_pk_fma_f32 v[62:63], v[62:63], v[202:203], v[234:235]
	v_cvt_pk_bf16_f32 v48, v48, v49
	v_cvt_pk_bf16_f32 v49, v50, v51
	v_cvt_pk_bf16_f32 v52, v52, v53
	v_cvt_pk_bf16_f32 v53, v54, v55
	v_cvt_pk_bf16_f32 v56, v56, v57
	v_cvt_pk_bf16_f32 v57, v58, v59
	v_cvt_pk_bf16_f32 v60, v60, v61
	v_cvt_pk_bf16_f32 v61, v62, v63
	global_store_dwordx2 v[182:183], v[48:49], off offset:0
	global_store_dwordx2 v[182:183], v[52:53], off offset:16
	global_store_dwordx2 v[182:183], v[56:57], off offset:32
	global_store_dwordx2 v[182:183], v[60:61], off offset:48
	v_lshl_add_u64 v[180:181], v[180:181], 0, s[48:49]
	global_load_dwordx4 v[220:223], v[180:181], off offset:0
	global_load_dwordx4 v[224:227], v[180:181], off offset:32
	global_load_dwordx4 v[228:231], v[180:181], off offset:64
	global_load_dwordx4 v[232:235], v[180:181], off offset:96
	s_waitcnt vmcnt(8)
	v_pk_fma_f32 v[32:33], v[32:33], v[204:205], v[236:237]
	v_pk_fma_f32 v[34:35], v[34:35], v[206:207], v[238:239]
	v_pk_fma_f32 v[36:37], v[36:37], v[208:209], v[244:245]
	v_pk_fma_f32 v[38:39], v[38:39], v[210:211], v[246:247]
	v_pk_fma_f32 v[40:41], v[40:41], v[212:213], v[248:249]
	v_pk_fma_f32 v[42:43], v[42:43], v[214:215], v[250:251]
	v_pk_fma_f32 v[44:45], v[44:45], v[216:217], v[252:253]
	v_pk_fma_f32 v[46:47], v[46:47], v[218:219], v[254:255]
	v_cvt_pk_bf16_f32 v32, v32, v33
	v_cvt_pk_bf16_f32 v33, v34, v35
	v_cvt_pk_bf16_f32 v36, v36, v37
	v_cvt_pk_bf16_f32 v37, v38, v39
	v_cvt_pk_bf16_f32 v40, v40, v41
	v_cvt_pk_bf16_f32 v41, v42, v43
	v_cvt_pk_bf16_f32 v44, v44, v45
	v_cvt_pk_bf16_f32 v45, v46, v47
	global_store_dwordx2 v[182:183], v[32:33], off offset:64
	global_store_dwordx2 v[182:183], v[36:37], off offset:80
	global_store_dwordx2 v[182:183], v[40:41], off offset:96
	global_store_dwordx2 v[182:183], v[44:45], off offset:112
	v_lshl_add_u64 v[182:183], v[182:183], 0, s[50:51]
	global_load_dwordx4 v[236:239], v[180:181], off offset:128
	global_load_dwordx4 v[244:247], v[180:181], off offset:160
	global_load_dwordx4 v[248:251], v[180:181], off offset:192
	global_load_dwordx4 v[252:255], v[180:181], off offset:224
	s_waitcnt vmcnt(8)
	v_pk_fma_f32 v[16:17], v[16:17], v[188:189], v[220:221]
	v_pk_fma_f32 v[18:19], v[18:19], v[190:191], v[222:223]
	v_pk_fma_f32 v[20:21], v[20:21], v[192:193], v[224:225]
	v_pk_fma_f32 v[22:23], v[22:23], v[194:195], v[226:227]
	v_pk_fma_f32 v[24:25], v[24:25], v[196:197], v[228:229]
	v_pk_fma_f32 v[26:27], v[26:27], v[198:199], v[230:231]
	v_pk_fma_f32 v[28:29], v[28:29], v[200:201], v[232:233]
	v_pk_fma_f32 v[30:31], v[30:31], v[202:203], v[234:235]
	v_cvt_pk_bf16_f32 v16, v16, v17
	v_cvt_pk_bf16_f32 v17, v18, v19
	v_cvt_pk_bf16_f32 v20, v20, v21
	v_cvt_pk_bf16_f32 v21, v22, v23
	v_cvt_pk_bf16_f32 v24, v24, v25
	v_cvt_pk_bf16_f32 v25, v26, v27
	v_cvt_pk_bf16_f32 v28, v28, v29
	v_cvt_pk_bf16_f32 v29, v30, v31
	global_store_dwordx2 v[182:183], v[16:17], off offset:0
	global_store_dwordx2 v[182:183], v[20:21], off offset:16
	global_store_dwordx2 v[182:183], v[24:25], off offset:32
	global_store_dwordx2 v[182:183], v[28:29], off offset:48
	s_waitcnt vmcnt(4)
	v_pk_fma_f32 v[0:1], v[0:1], v[204:205], v[236:237]
	v_pk_fma_f32 v[2:3], v[2:3], v[206:207], v[238:239]
	v_pk_fma_f32 v[4:5], v[4:5], v[208:209], v[244:245]
	v_pk_fma_f32 v[6:7], v[6:7], v[210:211], v[246:247]
	v_pk_fma_f32 v[8:9], v[8:9], v[212:213], v[248:249]
	v_pk_fma_f32 v[10:11], v[10:11], v[214:215], v[250:251]
	v_pk_fma_f32 v[12:13], v[12:13], v[216:217], v[252:253]
	v_pk_fma_f32 v[14:15], v[14:15], v[218:219], v[254:255]
	v_cvt_pk_bf16_f32 v0, v0, v1
	v_cvt_pk_bf16_f32 v1, v2, v3
	v_cvt_pk_bf16_f32 v4, v4, v5
	v_cvt_pk_bf16_f32 v5, v6, v7
	v_cvt_pk_bf16_f32 v8, v8, v9
	v_cvt_pk_bf16_f32 v9, v10, v11
	v_cvt_pk_bf16_f32 v12, v12, v13
	v_cvt_pk_bf16_f32 v13, v14, v15
	global_store_dwordx2 v[182:183], v[0:1], off offset:64
	global_store_dwordx2 v[182:183], v[4:5], off offset:80
	global_store_dwordx2 v[182:183], v[8:9], off offset:96
	global_store_dwordx2 v[182:183], v[12:13], off offset:112
	s_add_i32 s30, s30, s79
	s_add_i32 s31, s31, s34
	s_add_i32 s35, s35, s36
	s_cmp_gt_i32 s30, 63
	s_cbranch_scc1 .LBB0_168
